# stack + non-temporal stores for the two combine phases' outputs (less dirty L2 to write back at the following grid barrier)
# speedup vs baseline: 1.0066x; 1.0066x over previous
.LBB0_464:
	s_or_b64 exec, exec, s[8:9]
	v_div_scale_f32 v17, s[8:9], v16, v16, 1.0
	v_rcp_f32_e32 v24, v17
	v_div_scale_f32 v25, vcc, 1.0, v16, 1.0
	s_add_i32 s11, s11, s92
	v_fma_f32 v26, -v17, v24, 1.0
	v_fmac_f32_e32 v24, v26, v24
	v_mul_f32_e32 v26, v25, v24
	v_fma_f32 v27, -v17, v26, v25
	v_fmac_f32_e32 v26, v27, v24
	v_fma_f32 v17, -v17, v26, v25
	v_div_fmas_f32 v17, v17, v24, v26
	v_div_fixup_f32 v24, v17, v16, 1.0
	v_lshl_add_u64 v[26:27], s[20:21], 0, v[0:1]
	v_pk_mul_f32 v[18:19], v[24:25], v[18:19] op_sel_hi:[0,1]
	v_pk_mul_f32 v[14:15], v[24:25], v[14:15] op_sel_hi:[0,1]
	v_pk_mul_f32 v[6:7], v[24:25], v[6:7] op_sel_hi:[0,1]
	v_pk_mul_f32 v[16:17], v[24:25], v[22:23] op_sel_hi:[0,1]
	v_pk_mul_f32 v[20:21], v[24:25], v[20:21] op_sel_hi:[0,1]
	v_cvt_pk_bf16_f32 v18, v18, v19
	v_cvt_pk_bf16_f32 v19, v14, v15
	v_cvt_pk_bf16_f32 v15, v6, v7
	v_add_co_u32_e32 v6, vcc, 0x7100000, v26
	v_cvt_pk_bf16_f32 v16, v16, v17
	v_cvt_pk_bf16_f32 v17, v20, v21
	v_pk_mul_f32 v[12:13], v[24:25], v[12:13] op_sel_hi:[0,1]
	v_pk_mul_f32 v[10:11], v[24:25], v[10:11] op_sel_hi:[0,1]
	v_pk_mul_f32 v[8:9], v[24:25], v[8:9] op_sel_hi:[0,1]
	v_addc_co_u32_e32 v7, vcc, 0, v27, vcc
	v_lshl_add_u64 v[0:1], v[0:1], 0, s[0:1]
	v_lshl_add_u64 v[2:3], v[2:3], 0, s[2:3]
	s_cmpk_gt_i32 s11, 0x7fff
	v_lshl_add_u64 v[4:5], v[4:5], 0, s[6:7]
	v_cvt_pk_bf16_f32 v12, v12, v13
	v_cvt_pk_bf16_f32 v13, v10, v11
	v_cvt_pk_bf16_f32 v14, v8, v9
	global_store_dwordx4 v[6:7], v[16:19], off nt
	global_store_dwordx4 v[6:7], v[12:15], off offset:16 nt
	s_cbranch_scc1 .LBB0_473

.LBB0_939:
	s_and_saveexec_b64 s[30:31], s[0:1]
	s_cbranch_execz .LBB0_938
	v_lshl_add_u64 v[10:11], s[20:21], 0, v[2:3]
	v_add_co_u32_e32 v12, vcc, s33, v10
	v_lshl_add_u64 v[8:9], s[20:21], 0, v[0:1]
	s_nop 0
	v_addc_co_u32_e32 v13, vcc, 0, v11, vcc
	v_add_co_u32_e32 v8, vcc, 0x13100000, v8
	v_lshl_add_u64 v[10:11], v[10:11], 0, s[28:29]
	s_nop 0
	v_addc_co_u32_e32 v9, vcc, 0, v9, vcc
	global_load_dwordx4 v[4:7], v[12:13], off
	global_load_dword v21, v[8:9], off
	global_load_dword v22, v[8:9], off offset:16
	global_load_dword v23, v[8:9], off offset:32
	s_nop 0
	global_load_dwordx4 v[8:11], v[10:11], off offset:16
	s_waitcnt vmcnt(4)
	v_lshlrev_b32_e32 v14, 16, v4
	s_waitcnt vmcnt(1)
	v_max3_f32 v24, v21, v22, v23
	v_sub_f32_e32 v21, v21, v24
	v_sub_f32_e32 v22, v22, v24
	v_sub_f32_e32 v23, v23, v24
	v_exp_f32_e32 v22, v22
	v_exp_f32_e32 v23, v23
	v_exp_f32_e32 v24, v21
	v_and_b32_e32 v15, 0xffff0000, v4
	v_lshlrev_b32_e32 v4, 16, v5
	v_cndmask_b32_e64 v25, v23, v22, s[4:5]
	v_add_f32_e32 v22, v24, v22
	v_cndmask_b32_e64 v24, v25, v24, s[6:7]
	v_add_f32_e32 v22, v23, v22
	v_div_scale_f32 v23, s[36:37], v22, v22, v24
	v_rcp_f32_e32 v25, v23
	v_div_scale_f32 v26, vcc, v24, v22, v24
	v_and_b32_e32 v5, 0xffff0000, v5
	v_fma_f32 v27, -v23, v25, 1.0
	v_fmac_f32_e32 v25, v27, v25
	v_mul_f32_e32 v27, v26, v25
	v_fma_f32 v28, -v23, v27, v26
	v_fmac_f32_e32 v27, v28, v25
	v_fma_f32 v23, -v23, v27, v26
	v_div_fmas_f32 v23, v23, v25, v27
	v_lshlrev_b32_e32 v16, 16, v6
	v_and_b32_e32 v17, 0xffff0000, v6
	v_lshlrev_b32_e32 v6, 16, v7
	v_and_b32_e32 v7, 0xffff0000, v7
	v_div_fixup_f32 v22, v23, v22, v24
	s_waitcnt vmcnt(0)
	v_lshlrev_b32_e32 v18, 16, v8
	v_and_b32_e32 v19, 0xffff0000, v8
	v_lshlrev_b32_e32 v8, 16, v9
	v_and_b32_e32 v9, 0xffff0000, v9
	v_lshlrev_b32_e32 v20, 16, v10
	v_and_b32_e32 v21, 0xffff0000, v10
	v_lshlrev_b32_e32 v10, 16, v11
	v_and_b32_e32 v11, 0xffff0000, v11
	v_pk_mul_f32 v[14:15], v[22:23], v[14:15] op_sel_hi:[0,1]
	v_pk_mul_f32 v[24:25], v[22:23], v[4:5] op_sel_hi:[0,1]
	v_pk_mul_f32 v[16:17], v[22:23], v[16:17] op_sel_hi:[0,1]
	v_pk_mul_f32 v[26:27], v[22:23], v[6:7] op_sel_hi:[0,1]
	v_pk_mul_f32 v[18:19], v[22:23], v[18:19] op_sel_hi:[0,1]
	v_pk_mul_f32 v[28:29], v[22:23], v[8:9] op_sel_hi:[0,1]
	v_pk_mul_f32 v[20:21], v[22:23], v[20:21] op_sel_hi:[0,1]
	v_pk_mul_f32 v[22:23], v[22:23], v[10:11] op_sel_hi:[0,1]
	v_cvt_pk_bf16_f32 v4, v14, v15
	v_cvt_pk_bf16_f32 v5, v24, v25
	v_cvt_pk_bf16_f32 v6, v16, v17
	v_cvt_pk_bf16_f32 v7, v26, v27
	v_cvt_pk_bf16_f32 v8, v18, v19
	v_cvt_pk_bf16_f32 v9, v28, v29
	v_cvt_pk_bf16_f32 v10, v20, v21
	v_cvt_pk_bf16_f32 v11, v22, v23
	global_store_dwordx4 v[12:13], v[4:7], off nt
	global_store_dwordx4 v[12:13], v[8:11], off offset:16 nt
	s_branch .LBB0_938
